# SB1: first grid seam's 16-counter XCD census read in one round trip (16 loads + one wait) instead of 16 dependent round trips
# baseline (speedup 1.0000x reference)
; __device__ __forceinline__ unsigned xb_ld(unsigned* p)              { return __hip_atomic_load(p, __ATOMIC_RELAXED, __HIP_MEMORY_SCOPE_AGENT); }
; __device__ __forceinline__ void xcd_barrier_complete(unsigned* bar, unsigned x, unsigned& nloc, unsigned& nx) {
;     const unsigned G = gridDim.x * gridDim.y * gridDim.z;
;     unsigned sum, cnt, mine, sp = 0u;
;     for (;;) {
;         sum = 0u; cnt = 0u; mine = 0u;
; #pragma unroll 1
;         for (unsigned j = 0; j < 16; ++j) { const unsigned c = xb_ld(&bar[XB_XCNT(j)]); sum += c; cnt += (c > 0u) ? 1u : 0u; mine = (j == x) ? c : mine; }
;         if (sum == G) break;
;         __builtin_amdgcn_s_sleep(1);
;         if ((++sp & 255u) == 0u) { if (xb_ld(&bar[XB_TMO])) break; if (sp > XB_SPIN_CAP) { atomicAdd(&bar[XB_TMO], 1u); break; } }
;     }
;     nloc = mine > 0u ? mine : 1u; nx = cnt > 0u ? cnt : 1u;
; }
.LBB0_45:
	s_mov_b32 s4, s33
	s_mov_b32 s5, s48
	v_mov_b32_e32 v116, 0
	global_load_dword v100, v116, s[4:5] sc1
	global_load_dword v101, v116, s[4:5] offset:256 sc1
	global_load_dword v102, v116, s[4:5] offset:512 sc1
	global_load_dword v103, v116, s[4:5] offset:768 sc1
	global_load_dword v104, v116, s[4:5] offset:1024 sc1
	global_load_dword v105, v116, s[4:5] offset:1280 sc1
	global_load_dword v106, v116, s[4:5] offset:1536 sc1
	global_load_dword v107, v116, s[4:5] offset:1792 sc1
	global_load_dword v108, v116, s[4:5] offset:2048 sc1
	global_load_dword v109, v116, s[4:5] offset:2304 sc1
	global_load_dword v110, v116, s[4:5] offset:2560 sc1
	global_load_dword v111, v116, s[4:5] offset:2816 sc1
	global_load_dword v112, v116, s[4:5] offset:3072 sc1
	global_load_dword v113, v116, s[4:5] offset:3328 sc1
	global_load_dword v114, v116, s[4:5] offset:3584 sc1
	global_load_dword v115, v116, s[4:5] offset:3840 sc1
	s_waitcnt vmcnt(0)
	s_cmp_eq_u32 s9, 0x0
	s_cselect_b64 vcc, -1, 0
	v_cmp_ne_u32_e64 s[4:5], 0, v100
	v_add_u32_e32 v3, v100, v3
	s_nop 0
	v_addc_co_u32_e64 v2, s[4:5], 0, v2, s[4:5]
	v_cndmask_b32_e32 v1, v1, v100, vcc
	s_cmp_eq_u32 s9, 0x100
	s_cselect_b64 vcc, -1, 0
	v_cmp_ne_u32_e64 s[4:5], 0, v101
	v_add_u32_e32 v3, v101, v3
	s_nop 0
	v_addc_co_u32_e64 v2, s[4:5], 0, v2, s[4:5]
	v_cndmask_b32_e32 v1, v1, v101, vcc
	s_cmp_eq_u32 s9, 0x200
	s_cselect_b64 vcc, -1, 0
	v_cmp_ne_u32_e64 s[4:5], 0, v102
	v_add_u32_e32 v3, v102, v3
	s_nop 0
	v_addc_co_u32_e64 v2, s[4:5], 0, v2, s[4:5]
	v_cndmask_b32_e32 v1, v1, v102, vcc
	s_cmp_eq_u32 s9, 0x300
	s_cselect_b64 vcc, -1, 0
	v_cmp_ne_u32_e64 s[4:5], 0, v103
	v_add_u32_e32 v3, v103, v3
	s_nop 0
	v_addc_co_u32_e64 v2, s[4:5], 0, v2, s[4:5]
	v_cndmask_b32_e32 v1, v1, v103, vcc
	s_cmp_eq_u32 s9, 0x400
	s_cselect_b64 vcc, -1, 0
	v_cmp_ne_u32_e64 s[4:5], 0, v104
	v_add_u32_e32 v3, v104, v3
	s_nop 0
	v_addc_co_u32_e64 v2, s[4:5], 0, v2, s[4:5]
	v_cndmask_b32_e32 v1, v1, v104, vcc
	s_cmp_eq_u32 s9, 0x500
	s_cselect_b64 vcc, -1, 0
	v_cmp_ne_u32_e64 s[4:5], 0, v105
	v_add_u32_e32 v3, v105, v3
	s_nop 0
	v_addc_co_u32_e64 v2, s[4:5], 0, v2, s[4:5]
	v_cndmask_b32_e32 v1, v1, v105, vcc
	s_cmp_eq_u32 s9, 0x600
	s_cselect_b64 vcc, -1, 0
	v_cmp_ne_u32_e64 s[4:5], 0, v106
	v_add_u32_e32 v3, v106, v3
	s_nop 0
	v_addc_co_u32_e64 v2, s[4:5], 0, v2, s[4:5]
	v_cndmask_b32_e32 v1, v1, v106, vcc
	s_cmp_eq_u32 s9, 0x700
	s_cselect_b64 vcc, -1, 0
	v_cmp_ne_u32_e64 s[4:5], 0, v107
	v_add_u32_e32 v3, v107, v3
	s_nop 0
	v_addc_co_u32_e64 v2, s[4:5], 0, v2, s[4:5]
	v_cndmask_b32_e32 v1, v1, v107, vcc
	s_cmp_eq_u32 s9, 0x800
	s_cselect_b64 vcc, -1, 0
	v_cmp_ne_u32_e64 s[4:5], 0, v108
	v_add_u32_e32 v3, v108, v3
	s_nop 0
	v_addc_co_u32_e64 v2, s[4:5], 0, v2, s[4:5]
	v_cndmask_b32_e32 v1, v1, v108, vcc
	s_cmp_eq_u32 s9, 0x900
	s_cselect_b64 vcc, -1, 0
	v_cmp_ne_u32_e64 s[4:5], 0, v109
	v_add_u32_e32 v3, v109, v3
	s_nop 0
	v_addc_co_u32_e64 v2, s[4:5], 0, v2, s[4:5]
	v_cndmask_b32_e32 v1, v1, v109, vcc
	s_cmp_eq_u32 s9, 0xa00
	s_cselect_b64 vcc, -1, 0
	v_cmp_ne_u32_e64 s[4:5], 0, v110
	v_add_u32_e32 v3, v110, v3
	s_nop 0
	v_addc_co_u32_e64 v2, s[4:5], 0, v2, s[4:5]
	v_cndmask_b32_e32 v1, v1, v110, vcc
	s_cmp_eq_u32 s9, 0xb00
	s_cselect_b64 vcc, -1, 0
	v_cmp_ne_u32_e64 s[4:5], 0, v111
	v_add_u32_e32 v3, v111, v3
	s_nop 0
	v_addc_co_u32_e64 v2, s[4:5], 0, v2, s[4:5]
	v_cndmask_b32_e32 v1, v1, v111, vcc
	s_cmp_eq_u32 s9, 0xc00
	s_cselect_b64 vcc, -1, 0
	v_cmp_ne_u32_e64 s[4:5], 0, v112
	v_add_u32_e32 v3, v112, v3
	s_nop 0
	v_addc_co_u32_e64 v2, s[4:5], 0, v2, s[4:5]
	v_cndmask_b32_e32 v1, v1, v112, vcc
	s_cmp_eq_u32 s9, 0xd00
	s_cselect_b64 vcc, -1, 0
	v_cmp_ne_u32_e64 s[4:5], 0, v113
	v_add_u32_e32 v3, v113, v3
	s_nop 0
	v_addc_co_u32_e64 v2, s[4:5], 0, v2, s[4:5]
	v_cndmask_b32_e32 v1, v1, v113, vcc
	s_cmp_eq_u32 s9, 0xe00
	s_cselect_b64 vcc, -1, 0
	v_cmp_ne_u32_e64 s[4:5], 0, v114
	v_add_u32_e32 v3, v114, v3
	s_nop 0
	v_addc_co_u32_e64 v2, s[4:5], 0, v2, s[4:5]
	v_cndmask_b32_e32 v1, v1, v114, vcc
	s_cmp_eq_u32 s9, 0xf00
	s_cselect_b64 vcc, -1, 0
	v_cmp_ne_u32_e64 s[4:5], 0, v115
	v_add_u32_e32 v3, v115, v3
	s_nop 0
	v_addc_co_u32_e64 v2, s[4:5], 0, v2, s[4:5]
	v_cndmask_b32_e32 v1, v1, v115, vcc
	v_cmp_ne_u32_e32 vcc, s49, v3
	s_mov_b64 s[36:37], -1
	s_or_b64 s[34:35], s[34:35], exec
	s_and_saveexec_b64 s[4:5], vcc
	s_cbranch_execz .LBB0_43
	s_add_i32 s3, s3, 1
	s_and_b32 s36, s3, 0xff
	s_cmp_eq_u32 s36, 0
	s_cselect_b64 s[36:37], -1, 0
	s_mov_b64 s[44:45], -1
	s_and_b64 vcc, exec, s[36:37]
	s_sleep 1
	s_cbranch_vccz .LBB0_42
	v_mov_b64_e32 v[4:5], s[12:13]
	flat_load_dword v3, v[4:5] offset:512 sc1
	s_waitcnt vmcnt(0) lgkmcnt(0)
	v_cmp_eq_u32_e32 vcc, 0, v3
	s_and_saveexec_b64 s[46:47], vcc
	s_cbranch_execz .LBB0_41
	s_cmp_gt_u32 s3, 0x40000
	s_cselect_b64 s[50:51], -1, 0
	s_andn2_b64 s[36:37], s[36:37], exec
	s_and_b64 s[50:51], s[50:51], exec
	s_xor_b64 s[44:45], exec, -1
	s_or_b64 s[36:37], s[36:37], s[50:51]
	s_branch .LBB0_41
